# weight-conversion stores written through (sc0 sc1) so the attention-end barrier's L2 writeback has nothing left from them
# speedup vs baseline: 1.0069x; 1.0069x over previous
; #define LAS __attribute__((address_space(3)))
; #define LDS_WAIT() asm volatile("s_waitcnt lgkmcnt(0)" ::: "memory")
; __device__ __forceinline__ unsigned pk2(float lo, float hi) { pk2_f2_t v = {lo, hi}; pk2_b2_t b = __builtin_convertvector(v, pk2_b2_t); return __builtin_bit_cast(unsigned, b); }
; __device__ __forceinline__ void tr64_item(const float* W, int K, int N, int srccol, bf16* WT, int destrow0  , int k0, LAS unsigned char* scr, int lane) {
;     ...
;         for (int c = 0; c < 4; ++c) { v4u o; o.x = pk2(v[8 * c], v[8 * c + 1]); o.y = pk2(v[8 * c + 2], v[8 * c + 3]); o.z = pk2(v[8 * c + 4], v[8 * c + 5]); o.w = pk2(v[8 * c + 6], v[8 * c + 7]);
;             *(LAS v4u*)(scr + lane * 128 + (((4 * h + c) ^ (lane & 7)) << 4)) = o; } }
;     LDS_WAIT(); asm volatile("" ::: "memory");
;     const int r = lane >> 3, c = lane & 7;
; #pragma unroll
;     for (int j = 0; j < 8; ++j) { const int n = r + 8 * j; const v4u o = *(const LAS v4u*)(scr + n * 128 + ((c ^ (n & 7)) << 4));
;         *(v4u*)(WT + (size_t)(destrow0 + n) * K + k0 + 8 * c) = o; }
;     LDS_WAIT(); asm volatile("" ::: "memory");
.LBB0_889:
	s_or_b64 exec, exec, s[14:15]
	s_waitcnt vmcnt(0) lgkmcnt(0)
	v_cvt_pk_bf16_f32 v8, v8, v7
	v_cvt_pk_bf16_f32 v9, v10, v9
	v_cvt_pk_bf16_f32 v10, v12, v11
	v_cvt_pk_bf16_f32 v11, v14, v13
	v_xad_u32 v4, v2, 64, v6
	ds_write_b128 v4, v[8:11]
	v_cvt_pk_bf16_f32 v8, v16, v15
	v_cvt_pk_bf16_f32 v9, v18, v17
	v_cvt_pk_bf16_f32 v10, v20, v19
	v_cvt_pk_bf16_f32 v11, v22, v21
	v_xad_u32 v4, v2, s92, v6
	v_ashrrev_i32_e32 v12, 3, v1
	s_ashr_i32 s3, s2, 31
	ds_write_b128 v4, v[8:11]
	v_cvt_pk_bf16_f32 v8, v24, v23
	v_cvt_pk_bf16_f32 v9, v26, v25
	v_cvt_pk_bf16_f32 v10, v28, v27
	v_cvt_pk_bf16_f32 v11, v30, v29
	v_xad_u32 v4, v2, s81, v6
	v_xor_b32_e32 v1, v12, v1
	ds_write_b128 v4, v[8:11]
	v_cvt_pk_bf16_f32 v8, v32, v31
	v_cvt_pk_bf16_f32 v9, v34, v33
	v_cvt_pk_bf16_f32 v10, v36, v35
	v_cvt_pk_bf16_f32 v11, v38, v37
	v_xad_u32 v4, v2, s85, v6
	v_lshlrev_b32_e32 v1, 4, v1
	s_lshl_b64 s[2:3], s[2:3], 1
	ds_write_b128 v4, v[8:11]
	v_and_b32_e32 v1, 0x70, v1
	s_add_u32 s2, s56, s2
	s_waitcnt lgkmcnt(0)
	v_add_u32_e32 v1, s46, v1
	s_addc_u32 s3, s57, s3
	v_lshl_add_u64 v[8:9], s[2:3], 0, v[2:3]
	v_lshl_add_u32 v2, v12, 7, v1
	ds_read_b128 v[4:7], v2
	v_add_u32_e32 v10, s4, v12
	v_ashrrev_i32_e32 v11, 31, v10
	v_lshlrev_b64 v[10:11], 12, v[10:11]
	v_lshl_add_u64 v[10:11], v[8:9], 0, v[10:11]
	v_add_u32_e32 v2, 8, v12
	s_waitcnt lgkmcnt(0)
	flat_store_dwordx4 v[10:11], v[4:7] sc0 sc1
	v_add_u32_e32 v10, s4, v2
	v_ashrrev_i32_e32 v11, 31, v10
	v_lshl_add_u32 v4, v2, 7, v1
	ds_read_b128 v[4:7], v4
	v_lshlrev_b64 v[10:11], 12, v[10:11]
	v_lshl_add_u64 v[10:11], v[8:9], 0, v[10:11]
	v_add_u32_e32 v2, 16, v12
	s_waitcnt lgkmcnt(0)
	flat_store_dwordx4 v[10:11], v[4:7] sc0 sc1
	v_add_u32_e32 v10, s4, v2
	s_nop 0
	v_lshl_add_u32 v4, v2, 7, v1
	ds_read_b128 v[4:7], v4
	v_ashrrev_i32_e32 v11, 31, v10
	v_lshlrev_b64 v[10:11], 12, v[10:11]
	v_lshl_add_u64 v[10:11], v[8:9], 0, v[10:11]
	v_add_u32_e32 v2, 24, v12
	s_waitcnt lgkmcnt(0)
	flat_store_dwordx4 v[10:11], v[4:7] sc0 sc1
	v_add_u32_e32 v10, s4, v2
	v_ashrrev_i32_e32 v11, 31, v10
	v_lshl_add_u32 v4, v2, 7, v1
	ds_read_b128 v[4:7], v4
	v_lshlrev_b64 v[10:11], 12, v[10:11]
	v_lshl_add_u64 v[10:11], v[8:9], 0, v[10:11]
	v_add_u32_e32 v2, 32, v12
	s_waitcnt lgkmcnt(0)
	flat_store_dwordx4 v[10:11], v[4:7] sc0 sc1
	v_add_u32_e32 v10, s4, v2
	s_nop 0
	v_lshl_add_u32 v4, v2, 7, v1
	ds_read_b128 v[4:7], v4
	v_ashrrev_i32_e32 v11, 31, v10
	v_lshlrev_b64 v[10:11], 12, v[10:11]
	v_lshl_add_u64 v[10:11], v[8:9], 0, v[10:11]
	v_add_u32_e32 v2, 40, v12
	s_waitcnt lgkmcnt(0)
	flat_store_dwordx4 v[10:11], v[4:7] sc0 sc1
	v_add_u32_e32 v10, s4, v2
	v_ashrrev_i32_e32 v11, 31, v10
	v_lshl_add_u32 v4, v2, 7, v1
	ds_read_b128 v[4:7], v4
	v_lshlrev_b64 v[10:11], 12, v[10:11]
	v_lshl_add_u64 v[10:11], v[8:9], 0, v[10:11]
	v_add_u32_e32 v2, 48, v12
	s_waitcnt lgkmcnt(0)
	flat_store_dwordx4 v[10:11], v[4:7] sc0 sc1
	v_add_u32_e32 v10, s4, v2
	s_nop 0
	v_lshl_add_u32 v4, v2, 7, v1
	ds_read_b128 v[4:7], v4
	v_ashrrev_i32_e32 v11, 31, v10
	v_lshlrev_b64 v[10:11], 12, v[10:11]
	v_lshl_add_u64 v[10:11], v[8:9], 0, v[10:11]
	v_add_u32_e32 v2, 56, v12
	s_waitcnt lgkmcnt(0)
	flat_store_dwordx4 v[10:11], v[4:7] sc0 sc1
	v_lshl_add_u32 v1, v2, 7, v1
	ds_read_b128 v[4:7], v1
	v_add_u32_e32 v10, s4, v2
	v_ashrrev_i32_e32 v11, 31, v10
	v_lshlrev_b64 v[10:11], 12, v[10:11]
	v_lshl_add_u64 v[8:9], v[8:9], 0, v[10:11]
	s_waitcnt lgkmcnt(0)
	flat_store_dwordx4 v[8:9], v[4:7] sc0 sc1
	s_waitcnt lgkmcnt(0)

; #define LAS __attribute__((address_space(3)))
; #define LDS_WAIT() asm volatile("s_waitcnt lgkmcnt(0)" ::: "memory")
; __device__ __forceinline__ unsigned pk2(float lo, float hi) { pk2_f2_t v = {lo, hi}; pk2_b2_t b = __builtin_convertvector(v, pk2_b2_t); return __builtin_bit_cast(unsigned, b); }
; __device__ __forceinline__ void tr64_item(const float* W, int K, int N, int srccol, bf16* WT, int destrow0  , int k0, LAS unsigned char* scr, int lane) {
;     ...
;         for (int c = 0; c < 4; ++c) { v4u o; o.x = pk2(v[8 * c], v[8 * c + 1]); o.y = pk2(v[8 * c + 2], v[8 * c + 3]); o.z = pk2(v[8 * c + 4], v[8 * c + 5]); o.w = pk2(v[8 * c + 6], v[8 * c + 7]);
;             *(LAS v4u*)(scr + lane * 128 + (((4 * h + c) ^ (lane & 7)) << 4)) = o; } }
;     LDS_WAIT(); asm volatile("" ::: "memory");
;     const int r = lane >> 3, c = lane & 7;
; #pragma unroll
;     for (int j = 0; j < 8; ++j) { const int n = r + 8 * j; const v4u o = *(const LAS v4u*)(scr + n * 128 + ((c ^ (n & 7)) << 4));
;         *(v4u*)(WT + (size_t)(destrow0 + n) * K + k0 + 8 * c) = o; }
;     LDS_WAIT(); asm volatile("" ::: "memory");
.LBB0_1022:
	s_or_b64 exec, exec, s[20:21]
	s_waitcnt vmcnt(0) lgkmcnt(0)
	v_cvt_pk_bf16_f32 v8, v8, v7
	v_cvt_pk_bf16_f32 v9, v10, v9
	v_cvt_pk_bf16_f32 v10, v12, v11
	v_cvt_pk_bf16_f32 v11, v14, v13
	v_xad_u32 v4, v2, 64, v6
	ds_write_b128 v4, v[8:11]
	v_cvt_pk_bf16_f32 v8, v16, v15
	v_cvt_pk_bf16_f32 v9, v18, v17
	v_cvt_pk_bf16_f32 v10, v20, v19
	v_cvt_pk_bf16_f32 v11, v22, v21
	v_xad_u32 v4, v2, s92, v6
	ds_write_b128 v4, v[8:11]
	v_cvt_pk_bf16_f32 v8, v24, v23
	v_cvt_pk_bf16_f32 v9, v26, v25
	v_cvt_pk_bf16_f32 v10, v28, v27
	v_cvt_pk_bf16_f32 v11, v30, v29
	v_xad_u32 v4, v2, s81, v6
	ds_write_b128 v4, v[8:11]
	v_cvt_pk_bf16_f32 v8, v32, v31
	v_cvt_pk_bf16_f32 v9, v34, v33
	v_cvt_pk_bf16_f32 v10, v36, v35
	v_cvt_pk_bf16_f32 v11, v38, v37
	v_xad_u32 v4, v2, s85, v6
	v_ashrrev_i32_e32 v12, 3, v1
	ds_write_b128 v4, v[8:11]
	v_xor_b32_e32 v4, v12, v1
	v_lshlrev_b32_e32 v4, 4, v4
	v_and_b32_e32 v4, 0x70, v4
	s_waitcnt lgkmcnt(0)
	v_add_u32_e32 v13, s46, v4
	v_lshl_add_u32 v4, v12, 7, v13
	s_lshl_b64 s[8:9], s[18:19], 1
	ds_read_b128 v[4:7], v4
	s_add_u32 s8, s58, s8
	s_addc_u32 s9, s59, s9
	v_lshl_add_u64 v[8:9], s[8:9], 0, v[2:3]
	v_add_u32_e32 v2, s4, v12
	v_mad_i64_i32 v[10:11], s[8:9], v2, s89, v[8:9]
	v_add_u32_e32 v2, 8, v12
	s_waitcnt lgkmcnt(0)
	flat_store_dwordx4 v[10:11], v[4:7] sc0 sc1
	s_mov_b64 s[24:25], 0
	s_nop 0
	v_lshl_add_u32 v4, v2, 7, v13
	ds_read_b128 v[4:7], v4
	v_add_u32_e32 v2, s4, v2
	v_mad_i64_i32 v[10:11], s[8:9], v2, s89, v[8:9]
	v_add_u32_e32 v2, 16, v12
	s_waitcnt lgkmcnt(0)
	flat_store_dwordx4 v[10:11], v[4:7] sc0 sc1
	s_nop 1
	v_lshl_add_u32 v4, v2, 7, v13
	ds_read_b128 v[4:7], v4
	v_add_u32_e32 v2, s4, v2
	v_mad_i64_i32 v[10:11], s[8:9], v2, s89, v[8:9]
	v_add_u32_e32 v2, 24, v12
	s_waitcnt lgkmcnt(0)
	flat_store_dwordx4 v[10:11], v[4:7] sc0 sc1
	s_nop 1
	v_lshl_add_u32 v4, v2, 7, v13
	ds_read_b128 v[4:7], v4
	v_add_u32_e32 v2, s4, v2
	v_mad_i64_i32 v[10:11], s[8:9], v2, s89, v[8:9]
	v_add_u32_e32 v2, 32, v12
	s_waitcnt lgkmcnt(0)
	flat_store_dwordx4 v[10:11], v[4:7] sc0 sc1
	s_nop 1
	v_lshl_add_u32 v4, v2, 7, v13
	ds_read_b128 v[4:7], v4
	v_add_u32_e32 v2, s4, v2
	v_mad_i64_i32 v[10:11], s[8:9], v2, s89, v[8:9]
	v_add_u32_e32 v2, 40, v12
	s_waitcnt lgkmcnt(0)
	flat_store_dwordx4 v[10:11], v[4:7] sc0 sc1
	s_nop 1
	v_lshl_add_u32 v4, v2, 7, v13
	ds_read_b128 v[4:7], v4
	v_add_u32_e32 v2, s4, v2
	v_mad_i64_i32 v[10:11], s[8:9], v2, s89, v[8:9]
	v_add_u32_e32 v2, 48, v12
	s_waitcnt lgkmcnt(0)
	flat_store_dwordx4 v[10:11], v[4:7] sc0 sc1
	s_nop 1
	v_lshl_add_u32 v4, v2, 7, v13
	ds_read_b128 v[4:7], v4
	v_add_u32_e32 v2, s4, v2
	v_mad_i64_i32 v[10:11], s[8:9], v2, s89, v[8:9]
	v_add_u32_e32 v2, 56, v12
	s_waitcnt lgkmcnt(0)
	flat_store_dwordx4 v[10:11], v[4:7] sc0 sc1
	s_nop 1
	v_lshl_add_u32 v4, v2, 7, v13
	ds_read_b128 v[4:7], v4
	v_add_u32_e32 v2, s4, v2
	v_mad_i64_i32 v[8:9], s[8:9], v2, s89, v[8:9]
	s_waitcnt lgkmcnt(0)
	flat_store_dwordx4 v[8:9], v[4:7] sc0 sc1
	s_waitcnt lgkmcnt(0)

; #define LAS __attribute__((address_space(3)))
; #define LDS_WAIT() asm volatile("s_waitcnt lgkmcnt(0)" ::: "memory")
; __device__ __forceinline__ unsigned pk2(float lo, float hi) { pk2_f2_t v = {lo, hi}; pk2_b2_t b = __builtin_convertvector(v, pk2_b2_t); return __builtin_bit_cast(unsigned, b); }
; __device__ __forceinline__ void tr64_item(const float* W, int K, int N, int srccol, bf16* WT, int destrow0  , int k0, LAS unsigned char* scr, int lane) {
;     ...
;         for (int c = 0; c < 4; ++c) { v4u o; o.x = pk2(v[8 * c], v[8 * c + 1]); o.y = pk2(v[8 * c + 2], v[8 * c + 3]); o.z = pk2(v[8 * c + 4], v[8 * c + 5]); o.w = pk2(v[8 * c + 6], v[8 * c + 7]);
;             *(LAS v4u*)(scr + lane * 128 + (((4 * h + c) ^ (lane & 7)) << 4)) = o; } }
;     LDS_WAIT(); asm volatile("" ::: "memory");
;     const int r = lane >> 3, c = lane & 7;
; #pragma unroll
;     for (int j = 0; j < 8; ++j) { const int n = r + 8 * j; const v4u o = *(const LAS v4u*)(scr + n * 128 + ((c ^ (n & 7)) << 4));
;         *(v4u*)(WT + (size_t)(destrow0 + n) * K + k0 + 8 * c) = o; }
;     LDS_WAIT(); asm volatile("" ::: "memory");
.LBB0_1152:
	s_or_b64 exec, exec, s[16:17]
	s_waitcnt vmcnt(0) lgkmcnt(0)
	v_cvt_pk_bf16_f32 v8, v8, v7
	v_cvt_pk_bf16_f32 v9, v10, v9
	v_cvt_pk_bf16_f32 v10, v12, v11
	v_cvt_pk_bf16_f32 v11, v14, v13
	v_xad_u32 v4, v2, 64, v6
	ds_write_b128 v4, v[8:11]
	v_cvt_pk_bf16_f32 v8, v16, v15
	v_cvt_pk_bf16_f32 v9, v18, v17
	v_cvt_pk_bf16_f32 v10, v20, v19
	v_cvt_pk_bf16_f32 v11, v22, v21
	v_xad_u32 v4, v2, s92, v6
	ds_write_b128 v4, v[8:11]
	v_cvt_pk_bf16_f32 v8, v24, v23
	v_cvt_pk_bf16_f32 v9, v26, v25
	v_cvt_pk_bf16_f32 v10, v28, v27
	v_cvt_pk_bf16_f32 v11, v30, v29
	v_xad_u32 v4, v2, s81, v6
	ds_write_b128 v4, v[8:11]
	v_cvt_pk_bf16_f32 v8, v32, v31
	v_cvt_pk_bf16_f32 v9, v34, v33
	v_cvt_pk_bf16_f32 v10, v36, v35
	v_cvt_pk_bf16_f32 v11, v38, v37
	v_xad_u32 v4, v2, s85, v6
	v_ashrrev_i32_e32 v12, 3, v1
	s_lshl_b32 s7, s7, 6
	ds_write_b128 v4, v[8:11]
	v_xor_b32_e32 v4, v12, v1
	v_lshlrev_b32_e32 v4, 4, v4
	s_lshl_b32 s7, s7, 1
	v_and_b32_e32 v4, 0x70, v4
	s_add_u32 s8, s60, s7
	s_waitcnt lgkmcnt(0)
	v_add_u32_e32 v13, s46, v4
	s_addc_u32 s9, s61, 0
	v_lshl_add_u64 v[8:9], s[8:9], 0, v[2:3]
	v_lshl_add_u32 v2, v12, 7, v13
	ds_read_b128 v[4:7], v2
	v_add_u32_e32 v10, s4, v12
	v_ashrrev_i32_e32 v11, 31, v10
	v_lshlrev_b64 v[10:11], 12, v[10:11]
	v_lshl_add_u64 v[10:11], v[8:9], 0, v[10:11]
	v_add_u32_e32 v2, 8, v12
	s_waitcnt lgkmcnt(0)
	flat_store_dwordx4 v[10:11], v[4:7] sc0 sc1
	v_add_u32_e32 v10, s4, v2
	v_ashrrev_i32_e32 v11, 31, v10
	v_lshl_add_u32 v4, v2, 7, v13
	ds_read_b128 v[4:7], v4
	v_lshlrev_b64 v[10:11], 12, v[10:11]
	v_lshl_add_u64 v[10:11], v[8:9], 0, v[10:11]
	v_add_u32_e32 v2, 16, v12
	s_mov_b64 s[24:25], 0
	s_waitcnt lgkmcnt(0)
	flat_store_dwordx4 v[10:11], v[4:7] sc0 sc1
	v_add_u32_e32 v10, s4, v2
	v_ashrrev_i32_e32 v11, 31, v10
	v_lshl_add_u32 v4, v2, 7, v13
	ds_read_b128 v[4:7], v4
	v_lshlrev_b64 v[10:11], 12, v[10:11]
	v_lshl_add_u64 v[10:11], v[8:9], 0, v[10:11]
	v_add_u32_e32 v2, 24, v12
	s_waitcnt lgkmcnt(0)
	flat_store_dwordx4 v[10:11], v[4:7] sc0 sc1
	v_add_u32_e32 v10, s4, v2
	s_nop 0
	v_lshl_add_u32 v4, v2, 7, v13
	ds_read_b128 v[4:7], v4
	v_ashrrev_i32_e32 v11, 31, v10
	v_lshlrev_b64 v[10:11], 12, v[10:11]
	v_lshl_add_u64 v[10:11], v[8:9], 0, v[10:11]
	v_add_u32_e32 v2, 32, v12
	s_waitcnt lgkmcnt(0)
	flat_store_dwordx4 v[10:11], v[4:7] sc0 sc1
	v_add_u32_e32 v10, s4, v2
	v_ashrrev_i32_e32 v11, 31, v10
	v_lshl_add_u32 v4, v2, 7, v13
	ds_read_b128 v[4:7], v4
	v_lshlrev_b64 v[10:11], 12, v[10:11]
	v_lshl_add_u64 v[10:11], v[8:9], 0, v[10:11]
	v_add_u32_e32 v2, 40, v12
	s_waitcnt lgkmcnt(0)
	flat_store_dwordx4 v[10:11], v[4:7] sc0 sc1
	v_add_u32_e32 v10, s4, v2
	s_nop 0
	v_lshl_add_u32 v4, v2, 7, v13
	ds_read_b128 v[4:7], v4
	v_ashrrev_i32_e32 v11, 31, v10
	v_lshlrev_b64 v[10:11], 12, v[10:11]
	v_lshl_add_u64 v[10:11], v[8:9], 0, v[10:11]
	v_add_u32_e32 v2, 48, v12
	s_waitcnt lgkmcnt(0)
	flat_store_dwordx4 v[10:11], v[4:7] sc0 sc1
	v_add_u32_e32 v10, s4, v2
	v_ashrrev_i32_e32 v11, 31, v10
	v_lshl_add_u32 v4, v2, 7, v13
	ds_read_b128 v[4:7], v4
	v_lshlrev_b64 v[10:11], 12, v[10:11]
	v_lshl_add_u64 v[10:11], v[8:9], 0, v[10:11]
	v_add_u32_e32 v2, 56, v12
	s_waitcnt lgkmcnt(0)
	flat_store_dwordx4 v[10:11], v[4:7] sc0 sc1
	v_add_u32_e32 v10, s4, v2
	s_nop 0
	v_lshl_add_u32 v4, v2, 7, v13
	ds_read_b128 v[4:7], v4
	v_ashrrev_i32_e32 v11, 31, v10
	v_lshlrev_b64 v[10:11], 12, v[10:11]
	v_lshl_add_u64 v[8:9], v[8:9], 0, v[10:11]
	s_waitcnt lgkmcnt(0)
	flat_store_dwordx4 v[8:9], v[4:7] sc0 sc1
	s_waitcnt lgkmcnt(0)

; #define LAS __attribute__((address_space(3)))
; #define LDS_WAIT() asm volatile("s_waitcnt lgkmcnt(0)" ::: "memory")
; __device__ __forceinline__ unsigned pk2(float lo, float hi) { pk2_f2_t v = {lo, hi}; pk2_b2_t b = __builtin_convertvector(v, pk2_b2_t); return __builtin_bit_cast(unsigned, b); }
; __device__ __forceinline__ void tr64_item(const float* W, int K, int N, int srccol, bf16* WT, int destrow0  , int k0, LAS unsigned char* scr, int lane) {
;     ...
;         for (int c = 0; c < 4; ++c) { v4u o; o.x = pk2(v[8 * c], v[8 * c + 1]); o.y = pk2(v[8 * c + 2], v[8 * c + 3]); o.z = pk2(v[8 * c + 4], v[8 * c + 5]); o.w = pk2(v[8 * c + 6], v[8 * c + 7]);
;             *(LAS v4u*)(scr + lane * 128 + (((4 * h + c) ^ (lane & 7)) << 4)) = o; } }
;     LDS_WAIT(); asm volatile("" ::: "memory");
;     const int r = lane >> 3, c = lane & 7;
; #pragma unroll
;     for (int j = 0; j < 8; ++j) { const int n = r + 8 * j; const v4u o = *(const LAS v4u*)(scr + n * 128 + ((c ^ (n & 7)) << 4));
;         *(v4u*)(WT + (size_t)(destrow0 + n) * K + k0 + 8 * c) = o; }
;     LDS_WAIT(); asm volatile("" ::: "memory");
.LBB0_1282:
	s_or_b64 exec, exec, s[14:15]
	s_waitcnt vmcnt(0) lgkmcnt(0)
	v_cvt_pk_bf16_f32 v8, v8, v7
	v_cvt_pk_bf16_f32 v9, v10, v9
	v_cvt_pk_bf16_f32 v10, v12, v11
	v_cvt_pk_bf16_f32 v11, v14, v13
	v_xad_u32 v4, v2, 64, v6
	ds_write_b128 v4, v[8:11]
	v_cvt_pk_bf16_f32 v8, v16, v15
	v_cvt_pk_bf16_f32 v9, v18, v17
	v_cvt_pk_bf16_f32 v10, v20, v19
	v_cvt_pk_bf16_f32 v11, v22, v21
	v_xad_u32 v4, v2, s92, v6
	ds_write_b128 v4, v[8:11]
	v_cvt_pk_bf16_f32 v8, v24, v23
	v_cvt_pk_bf16_f32 v9, v26, v25
	v_cvt_pk_bf16_f32 v10, v28, v27
	v_cvt_pk_bf16_f32 v11, v30, v29
	v_xad_u32 v4, v2, s81, v6
	ds_write_b128 v4, v[8:11]
	v_cvt_pk_bf16_f32 v8, v32, v31
	v_cvt_pk_bf16_f32 v9, v34, v33
	v_cvt_pk_bf16_f32 v10, v36, v35
	v_cvt_pk_bf16_f32 v11, v38, v37
	v_xad_u32 v4, v2, s85, v6
	v_ashrrev_i32_e32 v12, 3, v1
	ds_write_b128 v4, v[8:11]
	v_xor_b32_e32 v4, v12, v1
	v_lshlrev_b32_e32 v4, 4, v4
	s_lshl_b64 s[8:9], s[18:19], 1
	v_and_b32_e32 v4, 0x70, v4
	s_add_u32 s8, s62, s8
	s_waitcnt lgkmcnt(0)
	v_add_u32_e32 v13, s46, v4
	s_addc_u32 s9, s63, s9
	v_lshl_add_u64 v[8:9], s[8:9], 0, v[2:3]
	v_lshl_add_u32 v2, v12, 7, v13
	ds_read_b128 v[4:7], v2
	v_add_u32_e32 v10, s4, v12
	v_ashrrev_i32_e32 v11, 31, v10
	v_lshlrev_b64 v[10:11], 12, v[10:11]
	v_lshl_add_u64 v[10:11], v[8:9], 0, v[10:11]
	v_add_u32_e32 v2, 8, v12
	s_waitcnt lgkmcnt(0)
	flat_store_dwordx4 v[10:11], v[4:7] sc0 sc1
	v_add_u32_e32 v10, s4, v2
	v_ashrrev_i32_e32 v11, 31, v10
	v_lshl_add_u32 v4, v2, 7, v13
	ds_read_b128 v[4:7], v4
	v_lshlrev_b64 v[10:11], 12, v[10:11]
	v_lshl_add_u64 v[10:11], v[8:9], 0, v[10:11]
	v_add_u32_e32 v2, 16, v12
	s_waitcnt lgkmcnt(0)
	flat_store_dwordx4 v[10:11], v[4:7] sc0 sc1
	v_add_u32_e32 v10, s4, v2
	s_nop 0
	v_lshl_add_u32 v4, v2, 7, v13
	ds_read_b128 v[4:7], v4
	v_ashrrev_i32_e32 v11, 31, v10
	v_lshlrev_b64 v[10:11], 12, v[10:11]
	v_lshl_add_u64 v[10:11], v[8:9], 0, v[10:11]
	v_add_u32_e32 v2, 24, v12
	s_waitcnt lgkmcnt(0)
	flat_store_dwordx4 v[10:11], v[4:7] sc0 sc1
	v_add_u32_e32 v10, s4, v2
	v_ashrrev_i32_e32 v11, 31, v10
	v_lshl_add_u32 v4, v2, 7, v13
	ds_read_b128 v[4:7], v4
	v_lshlrev_b64 v[10:11], 12, v[10:11]
	v_lshl_add_u64 v[10:11], v[8:9], 0, v[10:11]
	v_add_u32_e32 v2, 32, v12
	s_waitcnt lgkmcnt(0)
	flat_store_dwordx4 v[10:11], v[4:7] sc0 sc1
	v_add_u32_e32 v10, s4, v2
	s_nop 0
	v_lshl_add_u32 v4, v2, 7, v13
	ds_read_b128 v[4:7], v4
	v_ashrrev_i32_e32 v11, 31, v10
	v_lshlrev_b64 v[10:11], 12, v[10:11]
	v_lshl_add_u64 v[10:11], v[8:9], 0, v[10:11]
	v_add_u32_e32 v2, 40, v12
	s_waitcnt lgkmcnt(0)
	flat_store_dwordx4 v[10:11], v[4:7] sc0 sc1
	v_add_u32_e32 v10, s4, v2
	v_ashrrev_i32_e32 v11, 31, v10
	v_lshl_add_u32 v4, v2, 7, v13
	ds_read_b128 v[4:7], v4
	v_lshlrev_b64 v[10:11], 12, v[10:11]
	v_lshl_add_u64 v[10:11], v[8:9], 0, v[10:11]
	v_add_u32_e32 v2, 48, v12
	s_waitcnt lgkmcnt(0)
	flat_store_dwordx4 v[10:11], v[4:7] sc0 sc1
	v_add_u32_e32 v10, s4, v2
	s_nop 0
	v_lshl_add_u32 v4, v2, 7, v13
	ds_read_b128 v[4:7], v4
	v_ashrrev_i32_e32 v11, 31, v10
	v_lshlrev_b64 v[10:11], 12, v[10:11]
	v_lshl_add_u64 v[10:11], v[8:9], 0, v[10:11]
	v_add_u32_e32 v2, 56, v12
	s_waitcnt lgkmcnt(0)
	flat_store_dwordx4 v[10:11], v[4:7] sc0 sc1
	v_add_u32_e32 v10, s4, v2
	v_ashrrev_i32_e32 v11, 31, v10
	v_lshl_add_u32 v4, v2, 7, v13
	ds_read_b128 v[4:7], v4
	v_lshlrev_b64 v[10:11], 12, v[10:11]
	v_lshl_add_u64 v[8:9], v[8:9], 0, v[10:11]
	s_waitcnt lgkmcnt(0)
	flat_store_dwordx4 v[8:9], v[4:7] sc0 sc1
	s_waitcnt lgkmcnt(0)

; #define LAS __attribute__((address_space(3)))
; #define LDS_WAIT() asm volatile("s_waitcnt lgkmcnt(0)" ::: "memory")
; __device__ __forceinline__ unsigned pk2(float lo, float hi) { pk2_f2_t v = {lo, hi}; pk2_b2_t b = __builtin_convertvector(v, pk2_b2_t); return __builtin_bit_cast(unsigned, b); }
; __device__ __forceinline__ void tr64_item(const float* W, int K, int N, int srccol, bf16* WT, int destrow0  , int k0, LAS unsigned char* scr, int lane) {
;     ...
;         for (int c = 0; c < 4; ++c) { v4u o; o.x = pk2(v[8 * c], v[8 * c + 1]); o.y = pk2(v[8 * c + 2], v[8 * c + 3]); o.z = pk2(v[8 * c + 4], v[8 * c + 5]); o.w = pk2(v[8 * c + 6], v[8 * c + 7]);
;             *(LAS v4u*)(scr + lane * 128 + (((4 * h + c) ^ (lane & 7)) << 4)) = o; } }
;     LDS_WAIT(); asm volatile("" ::: "memory");
;     const int r = lane >> 3, c = lane & 7;
; #pragma unroll
;     for (int j = 0; j < 8; ++j) { const int n = r + 8 * j; const v4u o = *(const LAS v4u*)(scr + n * 128 + ((c ^ (n & 7)) << 4));
;         *(v4u*)(WT + (size_t)(destrow0 + n) * K + k0 + 8 * c) = o; }
;     LDS_WAIT(); asm volatile("" ::: "memory");
.LBB0_1454:
	s_or_b64 exec, exec, s[2:3]
	s_waitcnt vmcnt(0) lgkmcnt(0)
	v_cvt_pk_bf16_f32 v8, v8, v7
	v_cvt_pk_bf16_f32 v9, v10, v9
	v_cvt_pk_bf16_f32 v10, v12, v11
	v_cvt_pk_bf16_f32 v11, v14, v13
	v_xad_u32 v4, v2, 64, v6
	ds_write_b128 v4, v[8:11]
	v_cvt_pk_bf16_f32 v8, v16, v15
	v_cvt_pk_bf16_f32 v9, v18, v17
	v_cvt_pk_bf16_f32 v10, v20, v19
	v_cvt_pk_bf16_f32 v11, v22, v21
	v_xad_u32 v4, v2, s92, v6
	v_ashrrev_i32_e32 v12, 3, v1
	s_ashr_i32 s15, s14, 31
	ds_write_b128 v4, v[8:11]
	v_cvt_pk_bf16_f32 v8, v24, v23
	v_cvt_pk_bf16_f32 v9, v26, v25
	v_cvt_pk_bf16_f32 v10, v28, v27
	v_cvt_pk_bf16_f32 v11, v30, v29
	v_xad_u32 v4, v2, s81, v6
	v_xor_b32_e32 v1, v12, v1
	ds_write_b128 v4, v[8:11]
	v_cvt_pk_bf16_f32 v8, v32, v31
	v_cvt_pk_bf16_f32 v9, v34, v33
	v_cvt_pk_bf16_f32 v10, v36, v35
	v_cvt_pk_bf16_f32 v11, v38, v37
	v_xad_u32 v4, v2, s85, v6
	v_lshlrev_b32_e32 v1, 4, v1
	s_lshl_b64 s[2:3], s[14:15], 1
	ds_write_b128 v4, v[8:11]
	v_and_b32_e32 v1, 0x70, v1
	s_add_u32 s2, s43, s2
	s_waitcnt lgkmcnt(0)
	v_add_u32_e32 v1, s46, v1
	s_addc_u32 s3, s44, s3
	v_lshl_add_u64 v[8:9], s[2:3], 0, v[2:3]
	v_lshl_add_u32 v2, v12, 7, v1
	ds_read_b128 v[4:7], v2
	v_add_u32_e32 v10, s4, v12
	v_ashrrev_i32_e32 v11, 31, v10
	v_lshlrev_b64 v[10:11], 12, v[10:11]
	v_lshl_add_u64 v[10:11], v[8:9], 0, v[10:11]
	v_add_u32_e32 v2, 8, v12
	s_waitcnt lgkmcnt(0)
	flat_store_dwordx4 v[10:11], v[4:7] sc0 sc1
	v_add_u32_e32 v10, s4, v2
	v_ashrrev_i32_e32 v11, 31, v10
	v_lshl_add_u32 v4, v2, 7, v1
	ds_read_b128 v[4:7], v4
	v_lshlrev_b64 v[10:11], 12, v[10:11]
	v_lshl_add_u64 v[10:11], v[8:9], 0, v[10:11]
	v_add_u32_e32 v2, 16, v12
	s_waitcnt lgkmcnt(0)
	flat_store_dwordx4 v[10:11], v[4:7] sc0 sc1
	v_add_u32_e32 v10, s4, v2
	s_nop 0
	v_lshl_add_u32 v4, v2, 7, v1
	ds_read_b128 v[4:7], v4
	v_ashrrev_i32_e32 v11, 31, v10
	v_lshlrev_b64 v[10:11], 12, v[10:11]
	v_lshl_add_u64 v[10:11], v[8:9], 0, v[10:11]
	v_add_u32_e32 v2, 24, v12
	s_waitcnt lgkmcnt(0)
	flat_store_dwordx4 v[10:11], v[4:7] sc0 sc1
	v_add_u32_e32 v10, s4, v2
	v_ashrrev_i32_e32 v11, 31, v10
	v_lshl_add_u32 v4, v2, 7, v1
	ds_read_b128 v[4:7], v4
	v_lshlrev_b64 v[10:11], 12, v[10:11]
	v_lshl_add_u64 v[10:11], v[8:9], 0, v[10:11]
	v_add_u32_e32 v2, 32, v12
	s_waitcnt lgkmcnt(0)
	flat_store_dwordx4 v[10:11], v[4:7] sc0 sc1
	v_add_u32_e32 v10, s4, v2
	s_nop 0
	v_lshl_add_u32 v4, v2, 7, v1
	ds_read_b128 v[4:7], v4
	v_ashrrev_i32_e32 v11, 31, v10
	v_lshlrev_b64 v[10:11], 12, v[10:11]
	v_lshl_add_u64 v[10:11], v[8:9], 0, v[10:11]
	v_add_u32_e32 v2, 40, v12
	s_waitcnt lgkmcnt(0)
	flat_store_dwordx4 v[10:11], v[4:7] sc0 sc1
	v_add_u32_e32 v10, s4, v2
	v_ashrrev_i32_e32 v11, 31, v10
	v_lshl_add_u32 v4, v2, 7, v1
	ds_read_b128 v[4:7], v4
	v_lshlrev_b64 v[10:11], 12, v[10:11]
	v_lshl_add_u64 v[10:11], v[8:9], 0, v[10:11]
	v_add_u32_e32 v2, 48, v12
	s_waitcnt lgkmcnt(0)
	flat_store_dwordx4 v[10:11], v[4:7] sc0 sc1
	v_add_u32_e32 v10, s4, v2
	s_nop 0
	v_lshl_add_u32 v4, v2, 7, v1
	ds_read_b128 v[4:7], v4
	v_ashrrev_i32_e32 v11, 31, v10
	v_lshlrev_b64 v[10:11], 12, v[10:11]
	v_lshl_add_u64 v[10:11], v[8:9], 0, v[10:11]
	v_add_u32_e32 v2, 56, v12
	s_waitcnt lgkmcnt(0)
	flat_store_dwordx4 v[10:11], v[4:7] sc0 sc1
	v_lshl_add_u32 v1, v2, 7, v1
	ds_read_b128 v[4:7], v1
	v_add_u32_e32 v10, s4, v2
	v_ashrrev_i32_e32 v11, 31, v10
	v_lshlrev_b64 v[10:11], 12, v[10:11]
	v_lshl_add_u64 v[8:9], v[8:9], 0, v[10:11]
	s_waitcnt lgkmcnt(0)
	flat_store_dwordx4 v[8:9], v[4:7] sc0 sc1
	s_waitcnt lgkmcnt(0)

; #define LAS __attribute__((address_space(3)))
; #define LDS_WAIT() asm volatile("s_waitcnt lgkmcnt(0)" ::: "memory")
; __device__ __forceinline__ unsigned pk2(float lo, float hi) { pk2_f2_t v = {lo, hi}; pk2_b2_t b = __builtin_convertvector(v, pk2_b2_t); return __builtin_bit_cast(unsigned, b); }
; __device__ __forceinline__ void tr64_item(const float* W, int K, int N, int srccol, bf16* WT, int destrow0  , int k0, LAS unsigned char* scr, int lane) {
;     ...
;         for (int c = 0; c < 4; ++c) { v4u o; o.x = pk2(v[8 * c], v[8 * c + 1]); o.y = pk2(v[8 * c + 2], v[8 * c + 3]); o.z = pk2(v[8 * c + 4], v[8 * c + 5]); o.w = pk2(v[8 * c + 6], v[8 * c + 7]);
;             *(LAS v4u*)(scr + lane * 128 + (((4 * h + c) ^ (lane & 7)) << 4)) = o; } }
;     LDS_WAIT(); asm volatile("" ::: "memory");
;     const int r = lane >> 3, c = lane & 7;
; #pragma unroll
;     for (int j = 0; j < 8; ++j) { const int n = r + 8 * j; const v4u o = *(const LAS v4u*)(scr + n * 128 + ((c ^ (n & 7)) << 4));
;         *(v4u*)(WT + (size_t)(destrow0 + n) * K + k0 + 8 * c) = o; }
;     LDS_WAIT(); asm volatile("" ::: "memory");
.LBB0_1587:
	s_or_b64 exec, exec, s[20:21]
	s_waitcnt vmcnt(0) lgkmcnt(0)
	v_cvt_pk_bf16_f32 v8, v8, v7
	v_cvt_pk_bf16_f32 v9, v10, v9
	v_cvt_pk_bf16_f32 v10, v12, v11
	v_cvt_pk_bf16_f32 v11, v14, v13
	v_xad_u32 v4, v2, 64, v6
	ds_write_b128 v4, v[8:11]
	v_cvt_pk_bf16_f32 v8, v16, v15
	v_cvt_pk_bf16_f32 v9, v18, v17
	v_cvt_pk_bf16_f32 v10, v20, v19
	v_cvt_pk_bf16_f32 v11, v22, v21
	v_xad_u32 v4, v2, s92, v6
	ds_write_b128 v4, v[8:11]
	v_cvt_pk_bf16_f32 v8, v24, v23
	v_cvt_pk_bf16_f32 v9, v26, v25
	v_cvt_pk_bf16_f32 v10, v28, v27
	v_cvt_pk_bf16_f32 v11, v30, v29
	v_xad_u32 v4, v2, s81, v6
	ds_write_b128 v4, v[8:11]
	v_cvt_pk_bf16_f32 v8, v32, v31
	v_cvt_pk_bf16_f32 v9, v34, v33
	v_cvt_pk_bf16_f32 v10, v36, v35
	v_cvt_pk_bf16_f32 v11, v38, v37
	v_xad_u32 v4, v2, s85, v6
	v_ashrrev_i32_e32 v12, 3, v1
	ds_write_b128 v4, v[8:11]
	v_xor_b32_e32 v4, v12, v1
	v_lshlrev_b32_e32 v4, 4, v4
	v_and_b32_e32 v4, 0x70, v4
	s_waitcnt lgkmcnt(0)
	v_add_u32_e32 v13, s46, v4
	v_lshl_add_u32 v4, v12, 7, v13
	s_lshl_b64 s[8:9], s[18:19], 1
	ds_read_b128 v[4:7], v4
	s_add_u32 s8, s45, s8
	s_addc_u32 s9, s47, s9
	v_lshl_add_u64 v[8:9], s[8:9], 0, v[2:3]
	v_add_u32_e32 v2, s4, v12
	v_mad_i64_i32 v[10:11], s[8:9], v2, s89, v[8:9]
	v_add_u32_e32 v2, 8, v12
	s_waitcnt lgkmcnt(0)
	flat_store_dwordx4 v[10:11], v[4:7] sc0 sc1
	s_mov_b64 s[24:25], 0
	s_nop 0
	v_lshl_add_u32 v4, v2, 7, v13
	ds_read_b128 v[4:7], v4
	v_add_u32_e32 v2, s4, v2
	v_mad_i64_i32 v[10:11], s[8:9], v2, s89, v[8:9]
	v_add_u32_e32 v2, 16, v12
	s_waitcnt lgkmcnt(0)
	flat_store_dwordx4 v[10:11], v[4:7] sc0 sc1
	s_nop 1
	v_lshl_add_u32 v4, v2, 7, v13
	ds_read_b128 v[4:7], v4
	v_add_u32_e32 v2, s4, v2
	v_mad_i64_i32 v[10:11], s[8:9], v2, s89, v[8:9]
	v_add_u32_e32 v2, 24, v12
	s_waitcnt lgkmcnt(0)
	flat_store_dwordx4 v[10:11], v[4:7] sc0 sc1
	s_nop 1
	v_lshl_add_u32 v4, v2, 7, v13
	ds_read_b128 v[4:7], v4
	v_add_u32_e32 v2, s4, v2
	v_mad_i64_i32 v[10:11], s[8:9], v2, s89, v[8:9]
	v_add_u32_e32 v2, 32, v12
	s_waitcnt lgkmcnt(0)
	flat_store_dwordx4 v[10:11], v[4:7] sc0 sc1
	s_nop 1
	v_lshl_add_u32 v4, v2, 7, v13
	ds_read_b128 v[4:7], v4
	v_add_u32_e32 v2, s4, v2
	v_mad_i64_i32 v[10:11], s[8:9], v2, s89, v[8:9]
	v_add_u32_e32 v2, 40, v12
	s_waitcnt lgkmcnt(0)
	flat_store_dwordx4 v[10:11], v[4:7] sc0 sc1
	s_nop 1
	v_lshl_add_u32 v4, v2, 7, v13
	ds_read_b128 v[4:7], v4
	v_add_u32_e32 v2, s4, v2
	v_mad_i64_i32 v[10:11], s[8:9], v2, s89, v[8:9]
	v_add_u32_e32 v2, 48, v12
	s_waitcnt lgkmcnt(0)
	flat_store_dwordx4 v[10:11], v[4:7] sc0 sc1
	s_nop 1
	v_lshl_add_u32 v4, v2, 7, v13
	ds_read_b128 v[4:7], v4
	v_add_u32_e32 v2, s4, v2
	v_mad_i64_i32 v[10:11], s[8:9], v2, s89, v[8:9]
	v_add_u32_e32 v2, 56, v12
	s_waitcnt lgkmcnt(0)
	flat_store_dwordx4 v[10:11], v[4:7] sc0 sc1
	s_nop 1
	v_lshl_add_u32 v4, v2, 7, v13
	ds_read_b128 v[4:7], v4
	v_add_u32_e32 v2, s4, v2
	v_mad_i64_i32 v[8:9], s[8:9], v2, s89, v[8:9]
	s_waitcnt lgkmcnt(0)
	flat_store_dwordx4 v[8:9], v[4:7] sc0 sc1
	s_waitcnt lgkmcnt(0)

; #define LAS __attribute__((address_space(3)))
; #define LDS_WAIT() asm volatile("s_waitcnt lgkmcnt(0)" ::: "memory")
; __device__ __forceinline__ unsigned pk2(float lo, float hi) { pk2_f2_t v = {lo, hi}; pk2_b2_t b = __builtin_convertvector(v, pk2_b2_t); return __builtin_bit_cast(unsigned, b); }
; __device__ __forceinline__ void tr64_item(const float* W, int K, int N, int srccol, bf16* WT, int destrow0  , int k0, LAS unsigned char* scr, int lane) {
;     ...
;         for (int c = 0; c < 4; ++c) { v4u o; o.x = pk2(v[8 * c], v[8 * c + 1]); o.y = pk2(v[8 * c + 2], v[8 * c + 3]); o.z = pk2(v[8 * c + 4], v[8 * c + 5]); o.w = pk2(v[8 * c + 6], v[8 * c + 7]);
;             *(LAS v4u*)(scr + lane * 128 + (((4 * h + c) ^ (lane & 7)) << 4)) = o; } }
;     LDS_WAIT(); asm volatile("" ::: "memory");
;     const int r = lane >> 3, c = lane & 7;
; #pragma unroll
;     for (int j = 0; j < 8; ++j) { const int n = r + 8 * j; const v4u o = *(const LAS v4u*)(scr + n * 128 + ((c ^ (n & 7)) << 4));
;         *(v4u*)(WT + (size_t)(destrow0 + n) * K + k0 + 8 * c) = o; }
;     LDS_WAIT(); asm volatile("" ::: "memory");
.LBB0_1717:
	s_or_b64 exec, exec, s[16:17]
	s_waitcnt vmcnt(0) lgkmcnt(0)
	v_cvt_pk_bf16_f32 v8, v8, v7
	v_cvt_pk_bf16_f32 v9, v10, v9
	v_cvt_pk_bf16_f32 v10, v12, v11
	v_cvt_pk_bf16_f32 v11, v14, v13
	v_xad_u32 v4, v2, 64, v6
	ds_write_b128 v4, v[8:11]
	v_cvt_pk_bf16_f32 v8, v16, v15
	v_cvt_pk_bf16_f32 v9, v18, v17
	v_cvt_pk_bf16_f32 v10, v20, v19
	v_cvt_pk_bf16_f32 v11, v22, v21
	v_xad_u32 v4, v2, s92, v6
	ds_write_b128 v4, v[8:11]
	v_cvt_pk_bf16_f32 v8, v24, v23
	v_cvt_pk_bf16_f32 v9, v26, v25
	v_cvt_pk_bf16_f32 v10, v28, v27
	v_cvt_pk_bf16_f32 v11, v30, v29
	v_xad_u32 v4, v2, s81, v6
	ds_write_b128 v4, v[8:11]
	v_cvt_pk_bf16_f32 v8, v32, v31
	v_cvt_pk_bf16_f32 v9, v34, v33
	v_cvt_pk_bf16_f32 v10, v36, v35
	v_cvt_pk_bf16_f32 v11, v38, v37
	v_xad_u32 v4, v2, s85, v6
	v_ashrrev_i32_e32 v12, 3, v1
	s_lshl_b32 s7, s7, 6
	ds_write_b128 v4, v[8:11]
	v_xor_b32_e32 v4, v12, v1
	v_lshlrev_b32_e32 v4, 4, v4
	s_lshl_b32 s7, s7, 1
	v_and_b32_e32 v4, 0x70, v4
	s_add_u32 s8, s48, s7
	s_waitcnt lgkmcnt(0)
	v_add_u32_e32 v13, s46, v4
	s_addc_u32 s9, s49, 0
	v_lshl_add_u64 v[8:9], s[8:9], 0, v[2:3]
	v_lshl_add_u32 v2, v12, 7, v13
	ds_read_b128 v[4:7], v2
	v_add_u32_e32 v10, s4, v12
	v_ashrrev_i32_e32 v11, 31, v10
	v_lshlrev_b64 v[10:11], 12, v[10:11]
	v_lshl_add_u64 v[10:11], v[8:9], 0, v[10:11]
	v_add_u32_e32 v2, 8, v12
	s_waitcnt lgkmcnt(0)
	flat_store_dwordx4 v[10:11], v[4:7] sc0 sc1
	v_add_u32_e32 v10, s4, v2
	v_ashrrev_i32_e32 v11, 31, v10
	v_lshl_add_u32 v4, v2, 7, v13
	ds_read_b128 v[4:7], v4
	v_lshlrev_b64 v[10:11], 12, v[10:11]
	v_lshl_add_u64 v[10:11], v[8:9], 0, v[10:11]
	v_add_u32_e32 v2, 16, v12
	s_mov_b64 s[24:25], 0
	s_waitcnt lgkmcnt(0)
	flat_store_dwordx4 v[10:11], v[4:7] sc0 sc1
	v_add_u32_e32 v10, s4, v2
	v_ashrrev_i32_e32 v11, 31, v10
	v_lshl_add_u32 v4, v2, 7, v13
	ds_read_b128 v[4:7], v4
	v_lshlrev_b64 v[10:11], 12, v[10:11]
	v_lshl_add_u64 v[10:11], v[8:9], 0, v[10:11]
	v_add_u32_e32 v2, 24, v12
	s_waitcnt lgkmcnt(0)
	flat_store_dwordx4 v[10:11], v[4:7] sc0 sc1
	v_add_u32_e32 v10, s4, v2
	s_nop 0
	v_lshl_add_u32 v4, v2, 7, v13
	ds_read_b128 v[4:7], v4
	v_ashrrev_i32_e32 v11, 31, v10
	v_lshlrev_b64 v[10:11], 12, v[10:11]
	v_lshl_add_u64 v[10:11], v[8:9], 0, v[10:11]
	v_add_u32_e32 v2, 32, v12
	s_waitcnt lgkmcnt(0)
	flat_store_dwordx4 v[10:11], v[4:7] sc0 sc1
	v_add_u32_e32 v10, s4, v2
	v_ashrrev_i32_e32 v11, 31, v10
	v_lshl_add_u32 v4, v2, 7, v13
	ds_read_b128 v[4:7], v4
	v_lshlrev_b64 v[10:11], 12, v[10:11]
	v_lshl_add_u64 v[10:11], v[8:9], 0, v[10:11]
	v_add_u32_e32 v2, 40, v12
	s_waitcnt lgkmcnt(0)
	flat_store_dwordx4 v[10:11], v[4:7] sc0 sc1
	v_add_u32_e32 v10, s4, v2
	s_nop 0
	v_lshl_add_u32 v4, v2, 7, v13
	ds_read_b128 v[4:7], v4
	v_ashrrev_i32_e32 v11, 31, v10
	v_lshlrev_b64 v[10:11], 12, v[10:11]
	v_lshl_add_u64 v[10:11], v[8:9], 0, v[10:11]
	v_add_u32_e32 v2, 48, v12
	s_waitcnt lgkmcnt(0)
	flat_store_dwordx4 v[10:11], v[4:7] sc0 sc1
	v_add_u32_e32 v10, s4, v2
	v_ashrrev_i32_e32 v11, 31, v10
	v_lshl_add_u32 v4, v2, 7, v13
	ds_read_b128 v[4:7], v4
	v_lshlrev_b64 v[10:11], 12, v[10:11]
	v_lshl_add_u64 v[10:11], v[8:9], 0, v[10:11]
	v_add_u32_e32 v2, 56, v12
	s_waitcnt lgkmcnt(0)
	flat_store_dwordx4 v[10:11], v[4:7] sc0 sc1
	v_add_u32_e32 v10, s4, v2
	s_nop 0
	v_lshl_add_u32 v4, v2, 7, v13
	ds_read_b128 v[4:7], v4
	v_ashrrev_i32_e32 v11, 31, v10
	v_lshlrev_b64 v[10:11], 12, v[10:11]
	v_lshl_add_u64 v[8:9], v[8:9], 0, v[10:11]
	s_waitcnt lgkmcnt(0)
	flat_store_dwordx4 v[8:9], v[4:7] sc0 sc1
	s_waitcnt lgkmcnt(0)

; #define LAS __attribute__((address_space(3)))
; #define LDS_WAIT() asm volatile("s_waitcnt lgkmcnt(0)" ::: "memory")
; __device__ __forceinline__ unsigned pk2(float lo, float hi) { pk2_f2_t v = {lo, hi}; pk2_b2_t b = __builtin_convertvector(v, pk2_b2_t); return __builtin_bit_cast(unsigned, b); }
; __device__ __forceinline__ void tr64_item(const float* W, int K, int N, int srccol, bf16* WT, int destrow0  , int k0, LAS unsigned char* scr, int lane) {
;     ...
;         for (int c = 0; c < 4; ++c) { v4u o; o.x = pk2(v[8 * c], v[8 * c + 1]); o.y = pk2(v[8 * c + 2], v[8 * c + 3]); o.z = pk2(v[8 * c + 4], v[8 * c + 5]); o.w = pk2(v[8 * c + 6], v[8 * c + 7]);
;             *(LAS v4u*)(scr + lane * 128 + (((4 * h + c) ^ (lane & 7)) << 4)) = o; } }
;     LDS_WAIT(); asm volatile("" ::: "memory");
;     const int r = lane >> 3, c = lane & 7;
; #pragma unroll
;     for (int j = 0; j < 8; ++j) { const int n = r + 8 * j; const v4u o = *(const LAS v4u*)(scr + n * 128 + ((c ^ (n & 7)) << 4));
;         *(v4u*)(WT + (size_t)(destrow0 + n) * K + k0 + 8 * c) = o; }
;     LDS_WAIT(); asm volatile("" ::: "memory");
.LBB0_1847:
	s_or_b64 exec, exec, s[14:15]
	s_waitcnt vmcnt(0) lgkmcnt(0)
	v_cvt_pk_bf16_f32 v8, v8, v7
	v_cvt_pk_bf16_f32 v9, v10, v9
	v_cvt_pk_bf16_f32 v10, v12, v11
	v_cvt_pk_bf16_f32 v11, v14, v13
	v_xad_u32 v4, v2, 64, v6
	ds_write_b128 v4, v[8:11]
	v_cvt_pk_bf16_f32 v8, v16, v15
	v_cvt_pk_bf16_f32 v9, v18, v17
	v_cvt_pk_bf16_f32 v10, v20, v19
	v_cvt_pk_bf16_f32 v11, v22, v21
	v_xad_u32 v4, v2, s92, v6
	ds_write_b128 v4, v[8:11]
	v_cvt_pk_bf16_f32 v8, v24, v23
	v_cvt_pk_bf16_f32 v9, v26, v25
	v_cvt_pk_bf16_f32 v10, v28, v27
	v_cvt_pk_bf16_f32 v11, v30, v29
	v_xad_u32 v4, v2, s81, v6
	ds_write_b128 v4, v[8:11]
	v_cvt_pk_bf16_f32 v8, v32, v31
	v_cvt_pk_bf16_f32 v9, v34, v33
	v_cvt_pk_bf16_f32 v10, v36, v35
	v_cvt_pk_bf16_f32 v11, v38, v37
	v_xad_u32 v4, v2, s85, v6
	v_ashrrev_i32_e32 v12, 3, v1
	ds_write_b128 v4, v[8:11]
	v_xor_b32_e32 v4, v12, v1
	v_lshlrev_b32_e32 v4, 4, v4
	s_lshl_b64 s[8:9], s[18:19], 1
	v_and_b32_e32 v4, 0x70, v4
	s_add_u32 s8, s50, s8
	s_waitcnt lgkmcnt(0)
	v_add_u32_e32 v13, s46, v4
	s_addc_u32 s9, s51, s9
	v_lshl_add_u64 v[8:9], s[8:9], 0, v[2:3]
	v_lshl_add_u32 v2, v12, 7, v13
	ds_read_b128 v[4:7], v2
	v_add_u32_e32 v10, s4, v12
	v_ashrrev_i32_e32 v11, 31, v10
	v_lshlrev_b64 v[10:11], 12, v[10:11]
	v_lshl_add_u64 v[10:11], v[8:9], 0, v[10:11]
	v_add_u32_e32 v2, 8, v12
	s_waitcnt lgkmcnt(0)
	flat_store_dwordx4 v[10:11], v[4:7] sc0 sc1
	v_add_u32_e32 v10, s4, v2
	v_ashrrev_i32_e32 v11, 31, v10
	v_lshl_add_u32 v4, v2, 7, v13
	ds_read_b128 v[4:7], v4
	v_lshlrev_b64 v[10:11], 12, v[10:11]
	v_lshl_add_u64 v[10:11], v[8:9], 0, v[10:11]
	v_add_u32_e32 v2, 16, v12
	s_waitcnt lgkmcnt(0)
	flat_store_dwordx4 v[10:11], v[4:7] sc0 sc1
	v_add_u32_e32 v10, s4, v2
	s_nop 0
	v_lshl_add_u32 v4, v2, 7, v13
	ds_read_b128 v[4:7], v4
	v_ashrrev_i32_e32 v11, 31, v10
	v_lshlrev_b64 v[10:11], 12, v[10:11]
	v_lshl_add_u64 v[10:11], v[8:9], 0, v[10:11]
	v_add_u32_e32 v2, 24, v12
	s_waitcnt lgkmcnt(0)
	flat_store_dwordx4 v[10:11], v[4:7] sc0 sc1
	v_add_u32_e32 v10, s4, v2
	v_ashrrev_i32_e32 v11, 31, v10
	v_lshl_add_u32 v4, v2, 7, v13
	ds_read_b128 v[4:7], v4
	v_lshlrev_b64 v[10:11], 12, v[10:11]
	v_lshl_add_u64 v[10:11], v[8:9], 0, v[10:11]
	v_add_u32_e32 v2, 32, v12
	s_waitcnt lgkmcnt(0)
	flat_store_dwordx4 v[10:11], v[4:7] sc0 sc1
	v_add_u32_e32 v10, s4, v2
	s_nop 0
	v_lshl_add_u32 v4, v2, 7, v13
	ds_read_b128 v[4:7], v4
	v_ashrrev_i32_e32 v11, 31, v10
	v_lshlrev_b64 v[10:11], 12, v[10:11]
	v_lshl_add_u64 v[10:11], v[8:9], 0, v[10:11]
	v_add_u32_e32 v2, 40, v12
	s_waitcnt lgkmcnt(0)
	flat_store_dwordx4 v[10:11], v[4:7] sc0 sc1
	v_add_u32_e32 v10, s4, v2
	v_ashrrev_i32_e32 v11, 31, v10
	v_lshl_add_u32 v4, v2, 7, v13
	ds_read_b128 v[4:7], v4
	v_lshlrev_b64 v[10:11], 12, v[10:11]
	v_lshl_add_u64 v[10:11], v[8:9], 0, v[10:11]
	v_add_u32_e32 v2, 48, v12
	s_waitcnt lgkmcnt(0)
	flat_store_dwordx4 v[10:11], v[4:7] sc0 sc1
	v_add_u32_e32 v10, s4, v2
	s_nop 0
	v_lshl_add_u32 v4, v2, 7, v13
	ds_read_b128 v[4:7], v4
	v_ashrrev_i32_e32 v11, 31, v10
	v_lshlrev_b64 v[10:11], 12, v[10:11]
	v_lshl_add_u64 v[10:11], v[8:9], 0, v[10:11]
	v_add_u32_e32 v2, 56, v12
	s_waitcnt lgkmcnt(0)
	flat_store_dwordx4 v[10:11], v[4:7] sc0 sc1
	v_add_u32_e32 v10, s4, v2
	v_ashrrev_i32_e32 v11, 31, v10
	v_lshl_add_u32 v4, v2, 7, v13
	ds_read_b128 v[4:7], v4
	v_lshlrev_b64 v[10:11], 12, v[10:11]
	v_lshl_add_u64 v[8:9], v[8:9], 0, v[10:11]
	s_waitcnt lgkmcnt(0)
	flat_store_dwordx4 v[8:9], v[4:7] sc0 sc1
	s_waitcnt lgkmcnt(0)
